# LRU tile loop: next-tile x/z rows loaded by global_load_short_d16_hi straight into the f32 registers (no shifts), waits moved to points of use (x: loop top vmcnt(32), z: behind tile barrier vmcnt(19))
# speedup vs baseline: 1.0202x; 1.0202x over previous
.LBB0_927:
	s_cmp_lt_u32 s39, s25
	s_cselect_b64 s[28:29], -1, 0
	s_add_i32 s80, s80, 1
	s_cmp_lt_u32 s80, s30
	s_cselect_b64 s[26:27], -1, 0
	s_cmp_ge_u32 s39, s25
	s_cbranch_scc1 .LBB0_933
	s_waitcnt vmcnt(32)
	v_fma_f32 v98, v173, v144, v172
	v_fma_f32 v99, v173, v161, v172
	v_fmac_f32_e32 v98, v174, v161
	v_fmac_f32_e32 v99, v174, v160
	v_fmac_f32_e32 v98, v175, v160
	v_fmac_f32_e32 v99, v175, v129
	v_fmac_f32_e32 v98, v176, v129
	v_fmac_f32_e32 v99, v176, v128
	ds_write2st64_b32 v1, v98, v99 offset1:1
	v_fma_f32 v98, v173, v160, v172
	v_fma_f32 v99, v173, v129, v172
	v_fmac_f32_e32 v98, v174, v129
	v_fmac_f32_e32 v99, v174, v128
	v_fmac_f32_e32 v98, v175, v128
	v_fmac_f32_e32 v99, v175, v133
	v_fmac_f32_e32 v98, v176, v133
	v_fmac_f32_e32 v99, v176, v132
	ds_write2st64_b32 v1, v98, v99 offset0:2 offset1:3
	v_fma_f32 v98, v173, v128, v172
	v_fma_f32 v99, v173, v133, v172
	v_fmac_f32_e32 v98, v174, v133
	v_fmac_f32_e32 v99, v174, v132
	v_fmac_f32_e32 v98, v175, v132
	v_fmac_f32_e32 v99, v175, v137
	v_fmac_f32_e32 v98, v176, v137
	v_fmac_f32_e32 v99, v176, v136
	ds_write2st64_b32 v1, v98, v99 offset0:4 offset1:5
	v_fma_f32 v98, v173, v132, v172
	v_fma_f32 v99, v173, v137, v172
	v_fmac_f32_e32 v98, v174, v137
	v_fmac_f32_e32 v99, v174, v136
	v_fmac_f32_e32 v98, v175, v136
	v_fmac_f32_e32 v99, v175, v141
	v_fmac_f32_e32 v98, v176, v141
	v_fmac_f32_e32 v99, v176, v140
	ds_write2st64_b32 v1, v98, v99 offset0:6 offset1:7
	v_fma_f32 v98, v173, v136, v172
	v_fma_f32 v99, v173, v141, v172
	v_fmac_f32_e32 v98, v174, v141
	v_fmac_f32_e32 v99, v174, v140
	v_fmac_f32_e32 v98, v175, v140
	v_fmac_f32_e32 v99, v175, v147
	v_fmac_f32_e32 v98, v176, v147
	v_fmac_f32_e32 v99, v176, v146
	ds_write2st64_b32 v1, v98, v99 offset0:8 offset1:9
	v_fma_f32 v98, v173, v140, v172
	v_fma_f32 v99, v173, v147, v172
	v_fmac_f32_e32 v98, v174, v147
	v_fmac_f32_e32 v99, v174, v146
	v_fmac_f32_e32 v98, v175, v146
	v_fmac_f32_e32 v99, v175, v151
	v_fmac_f32_e32 v98, v176, v151
	v_fmac_f32_e32 v99, v176, v150
	ds_write2st64_b32 v1, v98, v99 offset0:10 offset1:11
	v_fma_f32 v98, v173, v146, v172
	v_fma_f32 v99, v173, v151, v172
	v_fmac_f32_e32 v98, v174, v151
	v_fmac_f32_e32 v99, v174, v150
	v_fmac_f32_e32 v98, v175, v150
	v_fmac_f32_e32 v99, v175, v154
	v_fmac_f32_e32 v98, v176, v154
	v_fmac_f32_e32 v99, v176, v155
	ds_write2st64_b32 v1, v98, v99 offset0:12 offset1:13
	v_fma_f32 v98, v173, v150, v172
	v_fma_f32 v99, v173, v154, v172
	v_fmac_f32_e32 v98, v174, v154
	v_fmac_f32_e32 v99, v174, v155
	v_fmac_f32_e32 v98, v175, v155
	v_fmac_f32_e32 v99, v175, v157
	v_mov_b32_e32 v144, v155
	v_fmac_f32_e32 v98, v176, v157
	v_fmac_f32_e32 v99, v176, v156
	s_cmp_lg_u32 s31, s39
	ds_write2st64_b32 v1, v98, v99 offset0:14 offset1:15
	s_cbranch_scc1 .LBB0_930
	s_load_dwordx2 s[54:55], s[40:41], 0xb8
	s_waitcnt lgkmcnt(0)
	s_add_u32 s54, s54, s38
	s_addc_u32 s55, s55, 0
	s_add_u32 s54, s54, s20
	s_addc_u32 s55, s55, s21
	v_lshl_add_u64 v[98:99], v[118:119], 2, s[54:55]
	v_add_co_u32_e32 v100, vcc, 0x1000, v98
	global_store_dword v[98:99], v155, off
	s_nop 0
	v_addc_co_u32_e32 v101, vcc, 0, v99, vcc
	v_add_co_u32_e32 v98, vcc, 0x2000, v98
	global_store_dword v[100:101], v157, off
	s_nop 0
	v_addc_co_u32_e32 v99, vcc, 0, v99, vcc
	global_store_dword v[98:99], v156, off
.LBB0_930:
	s_andn2_b64 vcc, exec, s[26:27]
	v_mov_b64_e32 v[160:161], v[156:157]
	s_cbranch_vccnz .LBB0_932
	v_add_co_u32_e32 v98, vcc, 0xfbe00000, v158
	s_nop 1
	v_addc_co_u32_e32 v99, vcc, -1, v159, vcc
	global_load_short_d16_hi v144, v[98:99], off offset:-2304 nt
	global_load_short_d16_hi v137, v[98:99], off offset:-1408 nt
	global_load_short_d16_hi v133, v[98:99], off offset:-1664 nt
	global_load_short_d16_hi v129, v[98:99], off offset:-1920 nt
	global_load_short_d16_hi v161, v[98:99], off offset:-2176 nt
	global_load_short_d16_hi v160, v[98:99], off offset:-2048 nt
	global_load_short_d16_hi v128, v[98:99], off offset:-1792 nt
	global_load_short_d16_hi v132, v[98:99], off offset:-1536 nt
	global_load_short_d16_hi v136, v[98:99], off offset:-1280 nt
	global_load_short_d16_hi v154, v[98:99], off offset:-384 nt
	global_load_short_d16_hi v151, v[98:99], off offset:-640 nt
	global_load_short_d16_hi v147, v[98:99], off offset:-896 nt
	global_load_short_d16_hi v141, v[98:99], off offset:-1152 nt
	global_load_short_d16_hi v140, v[98:99], off offset:-1024 nt
	global_load_short_d16_hi v146, v[98:99], off offset:-768 nt
	global_load_short_d16_hi v150, v[98:99], off offset:-512 nt
	global_load_short_d16_hi v155, v[98:99], off offset:-256 nt
	global_load_short_d16_hi v157, v[98:99], off offset:-128 nt
	global_load_short_d16_hi v156, v[98:99], off nt

.LBB0_934:
	s_and_b32 s54, s37, 0x400
	s_lshl_b32 s54, s54, 2
	s_add_i32 s54, s54, 0
	s_add_i32 s54, s54, 0x18000
	s_add_i32 s55, s54, s51
	v_lshlrev_b32_e32 v99, 2, v106
	v_add_u32_e32 v100, s55, v99
	ds_write2st64_b32 v100, v101, v98 offset1:1
	s_waitcnt lgkmcnt(0)
	v_add_u32_e32 v98, s54, v99
	s_waitcnt lgkmcnt(0)
	s_barrier
	ds_read2st64_b32 v[164:165], v98 offset1:1
	ds_read2st64_b32 v[168:169], v98 offset0:2 offset1:3
	ds_read2st64_b32 v[166:167], v98 offset0:4 offset1:5
	ds_read2st64_b32 v[162:163], v98 offset0:6 offset1:7
	ds_read2st64_b32 v[104:105], v98 offset0:8 offset1:9
	ds_read2st64_b32 v[102:103], v98 offset0:10 offset1:11
	ds_read2st64_b32 v[100:101], v98 offset0:12 offset1:13
	ds_read2st64_b32 v[98:99], v98 offset0:14 offset1:15
	s_andn2_b64 vcc, exec, s[26:27]
	s_cbranch_vccnz .Lp6_zwait_last
	s_waitcnt vmcnt(19)
	s_branch .Lp6_zwait_done

.Lp6_zwait_done:
	s_andn2_b64 vcc, exec, s[28:29]
	s_waitcnt lgkmcnt(7)
	v_fmac_f32_e32 v165, v177, v164
	s_cbranch_vccnz .LBB0_937
	v_cndmask_b32_e64 v145, v165, v177, s[4:5]
	s_waitcnt lgkmcnt(6)
	v_fma_f32 v164, v168, v145, v169
	v_cndmask_b32_e64 v145, v145, v164, s[18:19]
	s_waitcnt lgkmcnt(5)
	v_fma_f32 v164, v166, v145, v167
	v_cndmask_b32_e64 v145, v145, v164, s[16:17]
	s_waitcnt lgkmcnt(4)
	v_fma_f32 v164, v162, v145, v163
	v_cndmask_b32_e64 v145, v145, v164, s[14:15]
	s_waitcnt lgkmcnt(3)
	v_fma_f32 v164, v104, v145, v105
	v_cndmask_b32_e64 v145, v145, v164, s[12:13]
	s_waitcnt lgkmcnt(2)
	v_fma_f32 v164, v102, v145, v103
	v_cndmask_b32_e64 v145, v145, v164, s[10:11]
	s_waitcnt lgkmcnt(1)
	v_fma_f32 v164, v100, v145, v101
	v_cndmask_b32_e64 v145, v145, v164, s[8:9]
	s_waitcnt lgkmcnt(0)
	v_fma_f32 v164, v98, v145, v99
	v_cndmask_b32_e64 v145, v145, v164, s[6:7]
	ds_read2st64_b32 v[178:179], v1 offset0:32 offset1:33
	ds_read2st64_b32 v[180:181], v1 offset0:16 offset1:17
	ds_read2st64_b32 v[182:183], v1 offset0:18 offset1:19
	ds_read2st64_b32 v[186:187], v1 offset0:20 offset1:21
	ds_read2st64_b32 v[188:189], v1 offset0:22 offset1:23
	ds_read2st64_b32 v[190:191], v1 offset0:34 offset1:35
	ds_read2st64_b32 v[192:193], v1 offset0:36 offset1:37
	ds_read2st64_b32 v[194:195], v1 offset0:38 offset1:39
	s_waitcnt lgkmcnt(6)
	v_fma_f32 v145, v145, v180, v178
	v_fmac_f32_e32 v179, v145, v181
	v_mul_f32_e32 v164, v125, v145
	v_add_co_u32_e32 v196, vcc, s77, v158
	v_mul_f32_e32 v145, v124, v179
	s_nop 0
	v_addc_co_u32_e32 v197, vcc, -1, v159, vcc
	v_cvt_pk_bf16_f32 v145, v145, s0
	global_store_short v[196:197], v145, off offset:-1792
	s_waitcnt lgkmcnt(2)
	v_fma_f32 v145, v179, v182, v190
	v_cvt_pk_bf16_f32 v164, v164, s0
	v_fmac_f32_e32 v191, v145, v183
	global_store_short v[196:197], v164, off offset:-1920
	v_mul_f32_e32 v164, v127, v145
	v_mul_f32_e32 v145, v126, v191
	v_cvt_pk_bf16_f32 v145, v145, s0
	global_store_short v[196:197], v145, off offset:-1536
	s_waitcnt lgkmcnt(1)
	v_fma_f32 v145, v191, v186, v192
	v_cvt_pk_bf16_f32 v164, v164, s0
	v_fmac_f32_e32 v193, v145, v187
	global_store_short v[196:197], v164, off offset:-1664
	v_mul_f32_e32 v164, v131, v145
	v_mul_f32_e32 v145, v130, v193
	v_cvt_pk_bf16_f32 v145, v145, s0
	global_store_short v[196:197], v145, off offset:-1280
	s_waitcnt lgkmcnt(0)
	v_fma_f32 v145, v193, v188, v194
	v_cvt_pk_bf16_f32 v164, v164, s0
	v_fmac_f32_e32 v195, v145, v189
	global_store_short v[196:197], v164, off offset:-1408
	v_mul_f32_e32 v164, v135, v145
	v_mul_f32_e32 v145, v134, v195
	v_cvt_pk_bf16_f32 v164, v164, s0
	v_cvt_pk_bf16_f32 v145, v145, s0
	global_store_short v[196:197], v164, off offset:-1152
	global_store_short v[196:197], v145, off offset:-1024
	ds_read2st64_b32 v[178:179], v1 offset0:40 offset1:41
	ds_read2st64_b32 v[180:181], v1 offset0:24 offset1:25
	ds_read2st64_b32 v[182:183], v1 offset0:26 offset1:27
	ds_read2st64_b32 v[186:187], v1 offset0:28 offset1:29
	ds_read2st64_b32 v[188:189], v1 offset0:30 offset1:31
	ds_read2st64_b32 v[190:191], v1 offset0:42 offset1:43
	ds_read2st64_b32 v[192:193], v1 offset0:44 offset1:45
	ds_read2st64_b32 v[198:199], v1 offset0:46 offset1:47
	s_waitcnt lgkmcnt(6)
	v_fma_f32 v145, v195, v180, v178
	v_fmac_f32_e32 v179, v145, v181
	v_mul_f32_e32 v164, v139, v145
	v_mul_f32_e32 v145, v138, v179
	v_cvt_pk_bf16_f32 v145, v145, s0
	global_store_short v[196:197], v145, off offset:-768
	s_waitcnt lgkmcnt(2)
	v_fma_f32 v145, v179, v182, v190
	v_cvt_pk_bf16_f32 v164, v164, s0
	v_fmac_f32_e32 v191, v145, v183
	global_store_short v[196:197], v164, off offset:-896
	v_mul_f32_e32 v164, v143, v145
	v_mul_f32_e32 v145, v142, v191
	v_cvt_pk_bf16_f32 v145, v145, s0
	global_store_short v[196:197], v145, off offset:-512
	s_waitcnt lgkmcnt(1)
	v_fma_f32 v145, v191, v186, v192
	v_cvt_pk_bf16_f32 v164, v164, s0
	v_fmac_f32_e32 v193, v145, v187
	global_store_short v[196:197], v164, off offset:-640
	v_mul_f32_e32 v164, v149, v145
	v_mul_f32_e32 v145, v148, v193
	v_cvt_pk_bf16_f32 v145, v145, s0
	global_store_short v[196:197], v145, off offset:-256
	s_waitcnt lgkmcnt(0)
	v_fma_f32 v145, v193, v188, v198
	v_cvt_pk_bf16_f32 v164, v164, s0
	v_fmac_f32_e32 v199, v145, v189
	global_store_short v[196:197], v164, off offset:-384
	v_mul_f32_e32 v164, v153, v145
	v_mul_f32_e32 v145, v152, v199
	v_cvt_pk_bf16_f32 v164, v164, s0
	v_cvt_pk_bf16_f32 v145, v145, s0
	s_andn2_b64 vcc, exec, s[26:27]
	global_store_short v[196:197], v164, off offset:-128
	global_store_short v[196:197], v145, off
	s_cbranch_vccnz .LBB0_937
	global_load_short_d16_hi v135, v[158:159], off offset:-1152 nt
	global_load_short_d16_hi v131, v[158:159], off offset:-1408 nt
	global_load_short_d16_hi v127, v[158:159], off offset:-1664 nt
	global_load_short_d16_hi v125, v[158:159], off offset:-1920 nt
	global_load_short_d16_hi v124, v[158:159], off offset:-1792 nt
	global_load_short_d16_hi v126, v[158:159], off offset:-1536 nt
	global_load_short_d16_hi v130, v[158:159], off offset:-1280 nt
	global_load_short_d16_hi v134, v[158:159], off offset:-1024 nt
	global_load_short_d16_hi v153, v[158:159], off offset:-128 nt
	global_load_short_d16_hi v149, v[158:159], off offset:-384 nt
	global_load_short_d16_hi v143, v[158:159], off offset:-640 nt
	global_load_short_d16_hi v139, v[158:159], off offset:-896 nt
	global_load_short_d16_hi v138, v[158:159], off offset:-768 nt
	global_load_short_d16_hi v142, v[158:159], off offset:-512 nt
	global_load_short_d16_hi v148, v[158:159], off offset:-256 nt
	global_load_short_d16_hi v152, v[158:159], off nt
